# B/D banded attention: T5 bias + bound shift enter the QK MFMA as its C operand (aligned b128 rows from four shifted copies of the reversed bias table); 32 bias adds and 10 LDS reads per tile removed
# speedup vs baseline: 1.0128x; 1.0128x over previous
; #define LAS __attribute__((address_space(3)))
; __device__ __forceinline__ int otid() { int t = __builtin_amdgcn_workitem_id_x(); asm volatile("" : "+v"(t)); return t; }
; __global__ void __launch_bounds__(NTHREADS) mega_fwd(Params p) {
;     ...
;                             LAS float* sBias = (LAS float*)(lds + 49152); const int t2 = otid();
;                             if (t2 < 96 + 129 + 96) { const int d = t2 - 96; sBias[t2] = (d < 0 || d > a.maxdist) ? -INFINITY : biasd[bcol * SEQ + d * dil]; }
.LBB0_363:
	s_or_b64 exec, exec, s[0:1]
	v_lshl_add_u32 v2, v2, 2, 0
	s_waitcnt vmcnt(0)
	ds_write_b32 v2, v3 offset:49152
	v_sub_f32_e32 v3, v3, v110
	v_sub_u32_e32 v2, 0x16500, v2
	ds_write_b32 v2, v3
	ds_write_b32 v2, v3 offset:1348
	ds_write_b32 v2, v3 offset:2696
	ds_write_b32 v2, v3 offset:4044

; #define ATT_LOAD(kt) do { const long kb_ = (long)(kt) * 64; \
;         rk0 = *(const u32x4*)(a.k + (kb_ + kkey0) * a.k_rs + kpart0 * 8); \
;         if (DQK == 96 && tid < 256) rk1 = *(const u32x4*)(a.k + (kb_ + kkey1) * a.k_rs + kpart1 * 8); \
;         rv0 = *(const u32x2*)(a.v + (kb_ + 2 * vkp) * a.v_rs + vdg * 4); rv1 = *(const u32x2*)(a.v + (kb_ + 2 * vkp + 1) * a.v_rs + vdg * 4); } while (0)
; template <int DQK, int MODE>
; __device__ __forceinline__ void attn_unit(LAS unsigned char* lds, const AttnArgs& a, const unsigned char* lut) {
;     ...
;     float lsum[2]; lsum[0] = (lg == 0) ? a.l_init : 0.f; lsum[1] = lsum[0];
;     const float nb = -a.bound;
;     f32x4 o[2][4];
; #pragma unroll
;     for (int qt = 0; qt < 2; ++qt)
; #pragma unroll
;         for (int d = 0; d < 4; ++d) o[qt][d] = (f32x4){0.f, 0.f, 0.f, 0.f};
;     u32x4 rk0, rk1; u32x2 rv0, rv1;
;     const int kkey0 = tid / KCH, kpart0 = tid % KCH; const int kkey1 = (tid + 512) / KCH, kpart1 = (tid + 512) % KCH;
;     const int vkp = tid & 31, vdg = tid >> 5;
;     ...
;     ATT_LOAD(kt_lo);
;     ATT_STORE(0);
;     if (kt_lo < kt_hi) ATT_LOAD(kt_lo + 1);
;     unsigned long long mwn0 = 0ull, mwn1 = 0ull;
;     if (MODE == 2) { mwn0 = a.mask[(long)qi * 128 + kt_lo]; mwn1 = a.mask[(long)(qi + 16) * 128 + kt_lo]; }
;     __syncthreads();
.LBB0_366:
	v_cmp_eq_u32_e64 s[36:37], 0, v10
	s_mov_b64 s[54:55], -1
	s_cmp_le_i32 s13, s14
	v_cndmask_b32_e64 v120, 0, v0, s[36:37]
	v_lshlrev_b32_e32 v166, 2, v10
	s_waitcnt lgkmcnt(0)
	s_barrier
	s_cbranch_scc0 .LBB0_376
	s_lshl_b32 s1, s17, 1
	s_or_b32 s15, s18, 31
	s_sub_i32 s16, s18, s16
	s_and_b32 s1, s1, 0xffffff80
	s_add_u32 s1, s1, 0x102
	v_and_b32_e32 v5, 31, v8
	s_addc_u32 s17, 0, 0
	v_lshl_or_b32 v5, v5, 2, s1
	v_mad_u64_u32 v[8:9], s[20:21], s52, v5, v[6:7]
	v_mov_b32_e32 v5, s17
	s_lshl_b32 s17, s52, 7
	s_add_u32 s0, s0, 0x80
	v_mad_u32_u24 v9, s52, v5, v9
	v_or_b32_e32 v5, s0, v11
	s_addc_u32 s1, 0, 0
	v_mad_u64_u32 v[6:7], s[20:21], s76, v5, v[6:7]
	v_lshl_add_u64 v[124:125], s[56:57], 0, v[6:7]
	v_lshl_add_u64 v[2:3], s[0:1], 0, v[2:3]
	v_lshlrev_b64 v[6:7], 1, v[114:115]
	v_lshlrev_b32_e32 v0, 2, v10
	v_mad_u64_u32 v[6:7], s[0:1], s76, v2, v[6:7]
	v_add_u32_e32 v2, s18, v4
	v_sub_u32_e32 v2, v2, v0
	s_lshl_b32 s18, s13, 6
	v_subrev_u32_e32 v2, s18, v2
	v_readlane_b32 s0, v254, 33
	v_xor_b32_e32 v54, 0x80000000, v110
	v_mov_b32_e32 v121, v120
	v_mad_i32_i24 v7, s76, v3, v7
	v_lshl_add_u32 v115, v2, 2, s0
	v_mov_b32_e32 v2, 0
	v_lshlrev_b32_e32 v167, 3, v10
	v_mov_b32_e32 v55, v54
	v_mov_b32_e32 v56, v54
	v_mov_b32_e32 v57, v54
	v_mul_u32_u24_e32 v168, 0x90, v4
	v_and_b32_e32 v214, 3, v4
	v_mul_u32_u24_e32 v214, 0x544, v214
	v_add_u32_e32 v214, 0x223f4, v214
	v_lshl_add_u64 v[122:123], s[56:57], 0, v[8:9]
	v_lshl_add_u64 v[126:127], s[38:39], 0, v[6:7]
	s_mov_b64 s[0:1], 0
	s_mov_b32 s19, 0
	v_mov_b64_e32 v[128:129], v[120:121]
	v_mov_b32_e32 v3, v2
	v_mov_b32_e32 v4, v2
	v_mov_b32_e32 v5, v2
	v_mov_b32_e32 v6, v2
	v_mov_b32_e32 v7, v2
	v_mov_b32_e32 v8, v2
	v_mov_b32_e32 v9, v2
	v_mov_b32_e32 v10, v2
	v_mov_b32_e32 v11, v2
	v_mov_b32_e32 v12, v2
	v_mov_b32_e32 v13, v2
	v_mov_b32_e32 v14, v2
	v_mov_b32_e32 v15, v2
	v_mov_b32_e32 v16, v2
	v_mov_b32_e32 v17, v2
	v_mov_b32_e32 v18, v2
	v_mov_b32_e32 v19, v2
	v_mov_b32_e32 v20, v2
	v_mov_b32_e32 v21, v2
	v_mov_b32_e32 v22, v2
	v_mov_b32_e32 v23, v2
	v_mov_b32_e32 v24, v2
	v_mov_b32_e32 v25, v2
	v_mov_b32_e32 v46, v2
	v_mov_b32_e32 v47, v2
	v_mov_b32_e32 v48, v2
	v_mov_b32_e32 v49, v2
	v_mov_b32_e32 v50, v2
	v_mov_b32_e32 v51, v2
	v_mov_b32_e32 v52, v2
	v_mov_b32_e32 v53, v2
	v_mov_b32_e32 v59, v120
	v_mov_b32_e32 v58, v120
	s_branch .LBB0_369

; template <int DQK, int VAR> ...
;     ...
;         __builtin_amdgcn_sched_barrier(0);
;         __builtin_amdgcn_s_setprio(1);
; #pragma unroll
;         for (int c = 0; c < 2; ++c) {
;             s[0][ch * 2 + c] = (f32x4){sinit, sinit, sinit, sinit}; s[1][ch * 2 + c] = s[0][ch * 2 + c];
; #pragma unroll
;             for (int ks = 0; ks < DQK / 32; ++ks) {
;                 s[0][ch * 2 + c] = __builtin_amdgcn_mfma_f32_16x16x32_bf16(kfr[c][ks], qf[0][ks], s[0][ch * 2 + c], 0, 0, 0);
;                 s[1][ch * 2 + c] = __builtin_amdgcn_mfma_f32_16x16x32_bf16(kfr[c][ks], qf[1][ks], s[1][ch * 2 + c], 0, 0, 0);
;             }
;         }
;         __builtin_amdgcn_s_setprio(0);
;         __builtin_amdgcn_sched_barrier(0);
;     }
;     __builtin_amdgcn_s_setprio(0);
;     __builtin_amdgcn_sched_barrier(0);
; #pragma unroll
;     for (int kk = 0; kk < 2; ++kk)
; #pragma unroll
;         for (int dt = 0; dt < 4; ++dt) {
;             const LAS bf16_t* vp = sVt + (dt * 16 + lr) * VP + kk * 32 + lg * 4;
;             const u32x2 v0 = *(const LAS u32x2*)vp, v1 = *(const LAS u32x2*)(vp + 16);
;             vfr[kk][dt].x = v0.x; vfr[kk][dt].y = v0.y; vfr[kk][dt].z = v1.x; vfr[kk][dt].w = v1.y;
;         }
;     __builtin_amdgcn_sched_barrier(0);
; #pragma unroll
;     for (int qt = 0; qt < 2; ++qt) {
;         const int dq = qi + qt * 16 - key0 - lg * 4;
;         const LAS float* bp = sBias + (dq + 33);
;         float ps = 0.f;
; #pragma unroll
;         for (int c = 0; c < 4; ++c)
; #pragma unroll
;             for (int j = 0; j < 4; ++j) {
;                 float val = s[qt][c][j]; float pv;
;                 if (VAR == 0) pv = fexp2(val);
;                 else if (VAR == 1) { pv = fexp2(val); pv = (dq >= c * 16 + j) ? pv : 0.f; }
;                 else if (VAR == 2) { pv = fexp2(val + bp[63 - (c * 16 + j)]); }
;                 else if (VAR == 3) { pv = fexp2(val); pv = __uint_as_float(__float_as_uint(pv) & (unsigned)__builtin_amdgcn_sbfe((int)(c < 2 ? mlo[qt] : mhi[qt]), (c & 1) * 16 + j, 1)); }
;                 else { pv = fexp2(val + bp[63 - (c * 16 + j)]); pv = __uint_as_float(__float_as_uint(pv) & (unsigned)__builtin_amdgcn_sbfe((int)(c < 2 ? mlo[qt] : mhi[qt]), (c & 1) * 16 + j, 1)); }
;                 s[qt][c][j] = pv; ps += pv;
;             }
;         lsum[qt] += ps;
;     }
;     __builtin_amdgcn_s_setprio(1);
; #pragma unroll
.LBB0_373:
	s_cmp_gt_i32 s18, s15
	s_cselect_b64 s[22:23], -1, 0
	s_add_i32 s21, s18, 63
	s_cmp_lt_i32 s21, s16
	s_cselect_b64 s[38:39], -1, 0
	s_or_b64 s[22:23], s[22:23], s[38:39]
	s_and_b64 vcc, exec, s[22:23]
	s_cbranch_vccnz .LBB0_368
	s_mulk_i32 s20, 0x6000
	s_add_i32 s20, s20, 0
	v_add3_u32 v78, s20, v112, v168
	v_sub_u32_e32 v86, v214, v115
	ds_read_b128 v[180:183], v86 offset:64
	ds_read_b128 v[184:187], v86
	ds_read_b128 v[58:61], v78
	ds_read_b128 v[62:65], v78 offset:64
	ds_read_b128 v[188:191], v86 offset:128
	ds_read_b128 v[200:203], v86 offset:64
	ds_read_b128 v[66:69], v78 offset:2304
	ds_read_b128 v[70:73], v78 offset:2368
	ds_read_b128 v[218:221], v86 offset:192
	ds_read_b128 v[222:225], v86 offset:128
	ds_read_b128 v[230:233], v86 offset:256
	ds_read_b128 v[234:237], v86 offset:192
	s_setprio 1
	s_waitcnt lgkmcnt(9)
	v_mfma_f32_16x16x32_bf16 v[180:183], v[58:61], v[26:29], v[180:183]
	v_mfma_f32_16x16x32_bf16 v[184:187], v[58:61], v[34:37], v[184:187]
	ds_read_b128 v[74:77], v78 offset:4608
	ds_read_b128 v[82:85], v78 offset:4672
	ds_read_b128 v[86:89], v78 offset:6912
	ds_read_b128 v[98:101], v78 offset:6976
	s_waitcnt lgkmcnt(12)
	v_mfma_f32_16x16x32_bf16 v[180:183], v[62:65], v[30:33], v[180:183]
	v_mfma_f32_16x16x32_bf16 v[184:187], v[62:65], v[38:41], v[184:187]
	s_waitcnt lgkmcnt(9)
	v_mfma_f32_16x16x32_bf16 v[188:191], v[66:69], v[26:29], v[188:191]
	v_mfma_f32_16x16x32_bf16 v[200:203], v[66:69], v[34:37], v[200:203]
	s_waitcnt lgkmcnt(8)
	v_mfma_f32_16x16x32_bf16 v[188:191], v[70:73], v[30:33], v[188:191]
	v_mfma_f32_16x16x32_bf16 v[200:203], v[70:73], v[38:41], v[200:203]
	s_waitcnt lgkmcnt(3)
	v_mfma_f32_16x16x32_bf16 v[218:221], v[74:77], v[26:29], v[218:221]
	v_mfma_f32_16x16x32_bf16 v[222:225], v[74:77], v[34:37], v[222:225]
	s_waitcnt lgkmcnt(2)
	v_mfma_f32_16x16x32_bf16 v[218:221], v[82:85], v[30:33], v[218:221]
	v_mfma_f32_16x16x32_bf16 v[222:225], v[82:85], v[38:41], v[222:225]
	s_waitcnt lgkmcnt(1)
	v_mfma_f32_16x16x32_bf16 v[230:233], v[86:89], v[26:29], v[230:233]
	v_mfma_f32_16x16x32_bf16 v[234:237], v[86:89], v[34:37], v[234:237]
	s_waitcnt lgkmcnt(0)
	v_mfma_f32_16x16x32_bf16 v[230:233], v[98:101], v[30:33], v[230:233]
	v_mfma_f32_16x16x32_bf16 v[234:237], v[98:101], v[38:41], v[234:237]
	s_setprio 0
	v_mov_b32_e32 v86, v78
	ds_read_b128 v[58:61], v86 offset:14336
	ds_read_b128 v[66:69], v86 offset:16640
	ds_read_b128 v[74:77], v86 offset:18944
	ds_read_b128 v[82:85], v86 offset:21248
	ds_read_b128 v[62:65], v86 offset:14400
	ds_read_b128 v[70:73], v86 offset:16704
	ds_read_b128 v[78:81], v86 offset:19008
	ds_read_b128 v[86:89], v86 offset:21312
	v_exp_f32_e32 v130, v180
	v_exp_f32_e32 v131, v184
	v_exp_f32_e32 v132, v181
	v_exp_f32_e32 v133, v185
	v_exp_f32_e32 v134, v182
	v_exp_f32_e32 v135, v186
	v_pk_add_f32 v[90:91], v[130:131], v[132:133]
	v_exp_f32_e32 v136, v183
	v_exp_f32_e32 v137, v187
	v_pk_add_f32 v[90:91], v[90:91], v[134:135]
	v_exp_f32_e32 v138, v188
	v_exp_f32_e32 v139, v200
	v_pk_add_f32 v[90:91], v[90:91], v[136:137]
	v_exp_f32_e32 v140, v189
	v_exp_f32_e32 v141, v201
	v_pk_add_f32 v[90:91], v[90:91], v[138:139]
	v_exp_f32_e32 v142, v190
	v_exp_f32_e32 v143, v202
	v_pk_add_f32 v[90:91], v[90:91], v[140:141]
	v_exp_f32_e32 v144, v191
	v_exp_f32_e32 v145, v203
	v_pk_add_f32 v[90:91], v[90:91], v[142:143]
	v_exp_f32_e32 v146, v218
	v_exp_f32_e32 v147, v222
	v_pk_add_f32 v[90:91], v[90:91], v[144:145]
	v_exp_f32_e32 v148, v219
	v_exp_f32_e32 v149, v223
	v_pk_add_f32 v[90:91], v[90:91], v[146:147]
	v_exp_f32_e32 v150, v220
	v_exp_f32_e32 v151, v224
	v_pk_add_f32 v[90:91], v[90:91], v[148:149]
	v_exp_f32_e32 v152, v221
	v_exp_f32_e32 v153, v225
	v_pk_add_f32 v[90:91], v[90:91], v[150:151]
	v_exp_f32_e32 v154, v230
	v_exp_f32_e32 v155, v234
	v_pk_add_f32 v[90:91], v[90:91], v[152:153]
	v_exp_f32_e32 v156, v231
	v_exp_f32_e32 v157, v235
	v_pk_add_f32 v[90:91], v[90:91], v[154:155]
	v_exp_f32_e32 v158, v232
	v_exp_f32_e32 v159, v236
	v_pk_add_f32 v[90:91], v[90:91], v[156:157]
	v_exp_f32_e32 v160, v233
	v_exp_f32_e32 v161, v237
	v_pk_add_f32 v[90:91], v[90:91], v[158:159]
	s_nop 0
	v_pk_add_f32 v[90:91], v[90:91], v[160:161]
	s_nop 0
	v_pk_add_f32 v[128:129], v[128:129], v[90:91]
	s_setprio 1
	v_cvt_pk_bf16_f32 v90, v130, v132
	v_cvt_pk_bf16_f32 v91, v134, v136
	v_cvt_pk_bf16_f32 v92, v138, v140
	v_cvt_pk_bf16_f32 v93, v142, v144
	v_cvt_pk_bf16_f32 v94, v131, v133
	v_cvt_pk_bf16_f32 v95, v135, v137
	v_cvt_pk_bf16_f32 v96, v139, v141
	v_cvt_pk_bf16_f32 v97, v143, v145
	s_waitcnt lgkmcnt(7)
	v_mfma_f32_16x16x32_bf16 v[50:53], v[58:61], v[90:93], v[50:53]
	v_mfma_f32_16x16x32_bf16 v[14:17], v[58:61], v[94:97], v[14:17]
	s_waitcnt lgkmcnt(6)
	v_mfma_f32_16x16x32_bf16 v[46:49], v[66:69], v[90:93], v[46:49]
	v_mfma_f32_16x16x32_bf16 v[10:13], v[66:69], v[94:97], v[10:13]
	v_cvt_pk_bf16_f32 v98, v146, v148
	v_cvt_pk_bf16_f32 v99, v150, v152
	v_cvt_pk_bf16_f32 v100, v154, v156
	v_cvt_pk_bf16_f32 v101, v158, v160
	s_waitcnt lgkmcnt(5)
	v_mfma_f32_16x16x32_bf16 v[22:25], v[74:77], v[90:93], v[22:25]
	v_mfma_f32_16x16x32_bf16 v[6:9], v[74:77], v[94:97], v[6:9]
	v_cvt_pk_bf16_f32 v102, v147, v149
	v_cvt_pk_bf16_f32 v103, v151, v153
	v_cvt_pk_bf16_f32 v104, v155, v157
	v_cvt_pk_bf16_f32 v105, v159, v161
	s_waitcnt lgkmcnt(4)
	v_mfma_f32_16x16x32_bf16 v[18:21], v[82:85], v[90:93], v[18:21]
	v_mfma_f32_16x16x32_bf16 v[2:5], v[82:85], v[94:97], v[2:5]
	s_waitcnt lgkmcnt(3)
	v_mfma_f32_16x16x32_bf16 v[50:53], v[62:65], v[98:101], v[50:53]
	v_mfma_f32_16x16x32_bf16 v[14:17], v[62:65], v[102:105], v[14:17]
	s_waitcnt lgkmcnt(2)
	v_mfma_f32_16x16x32_bf16 v[46:49], v[70:73], v[98:101], v[46:49]
	v_mfma_f32_16x16x32_bf16 v[10:13], v[70:73], v[102:105], v[10:13]
	s_waitcnt lgkmcnt(1)
	v_mfma_f32_16x16x32_bf16 v[22:25], v[78:81], v[98:101], v[22:25]
	v_mfma_f32_16x16x32_bf16 v[6:9], v[78:81], v[102:105], v[6:9]
	s_waitcnt lgkmcnt(0)
	v_mfma_f32_16x16x32_bf16 v[18:21], v[86:89], v[98:101], v[18:21]
	v_mfma_f32_16x16x32_bf16 v[2:5], v[86:89], v[102:105], v[2:5]
	s_setprio 0
	v_mov_b32_e32 v59, v128
	v_mov_b32_e32 v58, v129
	s_branch .LBB0_368
